# gates epilogue: explicit v_rndne before v_cvt_pk_u8_f32 dropped (instruction verified on chip to round to nearest even, incl. ties)
# speedup vs baseline: 1.0039x; 1.0032x over previous
.LBB0_394:
	v_mul_f32_e32 v146, 0xbfb8aa3b, v122
	v_mul_f32_e32 v147, 0xbfb8aa3b, v118
	v_mul_f32_e32 v148, 0xbfb8aa3b, v123
	v_mul_f32_e32 v149, 0xbfb8aa3b, v119
	v_mul_f32_e32 v150, 0xbfb8aa3b, v124
	v_mul_f32_e32 v151, 0xbfb8aa3b, v120
	v_mul_f32_e32 v155, 0xbfb8aa3b, v125
	v_mul_f32_e32 v156, 0xbfb8aa3b, v121
	v_mul_f32_e32 v157, 0xbfb8aa3b, v102
	v_mul_f32_e32 v158, 0xbfb8aa3b, v98
	v_mul_f32_e32 v159, 0xbfb8aa3b, v103
	v_mul_f32_e32 v160, 0xbfb8aa3b, v99
	v_mul_f32_e32 v161, 0xbfb8aa3b, v104
	v_mul_f32_e32 v170, 0xbfb8aa3b, v100
	v_mul_f32_e32 v185, 0xbfb8aa3b, v105
	v_mul_f32_e32 v186, 0xbfb8aa3b, v101
	v_mul_f32_e32 v187, 0xbfb8aa3b, v86
	v_mul_f32_e32 v188, 0xbfb8aa3b, v82
	v_mul_f32_e32 v189, 0xbfb8aa3b, v87
	v_mul_f32_e32 v191, 0xbfb8aa3b, v83
	v_mul_f32_e32 v205, 0xbfb8aa3b, v88
	v_mul_f32_e32 v206, 0xbfb8aa3b, v84
	v_mul_f32_e32 v219, 0xbfb8aa3b, v89
	v_mul_f32_e32 v220, 0xbfb8aa3b, v85
	v_mul_f32_e32 v221, 0xbfb8aa3b, v70
	v_mul_f32_e32 v222, 0xbfb8aa3b, v66
	v_mul_f32_e32 v223, 0xbfb8aa3b, v71
	v_mul_f32_e32 v224, 0xbfb8aa3b, v67
	v_mul_f32_e32 v225, 0xbfb8aa3b, v72
	v_mul_f32_e32 v226, 0xbfb8aa3b, v68
	v_mul_f32_e32 v227, 0xbfb8aa3b, v73
	v_mul_f32_e32 v228, 0xbfb8aa3b, v69
	v_exp_f32_e32 v217, v146
	v_exp_f32_e32 v152, v147
	v_exp_f32_e32 v218, v148
	v_exp_f32_e32 v153, v149
	v_exp_f32_e32 v154, v150
	v_exp_f32_e32 v150, v151
	v_exp_f32_e32 v155, v155
	v_exp_f32_e32 v151, v156
	v_exp_f32_e32 v215, v157
	v_exp_f32_e32 v211, v158
	v_exp_f32_e32 v216, v159
	v_exp_f32_e32 v212, v160
	v_exp_f32_e32 v213, v161
	v_exp_f32_e32 v209, v170
	v_exp_f32_e32 v214, v185
	v_exp_f32_e32 v210, v186
	v_exp_f32_e32 v207, v187
	v_exp_f32_e32 v190, v188
	v_exp_f32_e32 v208, v189
	v_exp_f32_e32 v191, v191
	v_exp_f32_e32 v205, v205
	v_exp_f32_e32 v156, v206
	v_exp_f32_e32 v206, v219
	v_exp_f32_e32 v157, v220
	v_exp_f32_e32 v188, v221
	v_exp_f32_e32 v160, v222
	v_exp_f32_e32 v189, v223
	v_exp_f32_e32 v161, v224
	v_exp_f32_e32 v186, v225
	v_exp_f32_e32 v158, v226
	v_exp_f32_e32 v187, v227
	v_exp_f32_e32 v159, v228
	s_cmp_gt_u32 s72, 16
	v_ashrrev_i32_e32 v185, 31, v184
	s_cbranch_scc0 .LBB0_414
	s_sub_i32 s2, s72, 17
	s_cmp_lt_u32 s2, 4
	s_mov_b32 s0, 0xb600000
	s_cselect_b32 s0, s0, 0xb600400
	v_readlane_b32 s6, v246, 2
	v_readlane_b32 s7, v246, 3
	s_add_u32 s0, s6, s0
	s_addc_u32 s1, s7, 0
	s_lshl_b32 s2, s2, 8
	s_and_b32 s2, s2, 0x300
	v_or_b32_e32 v170, s2, v175
	v_lshl_add_u64 v[148:149], s[0:1], 0, v[170:171]
	v_mul_f32_e32 v170, 0xbfb8aa3b, v130
	v_exp_f32_e32 v170, v170
	v_mul_f32_e32 v220, 0xbfb8aa3b, v131
	v_exp_f32_e32 v220, v220
	v_mul_f32_e32 v222, 0xbfb8aa3b, v132
	v_exp_f32_e32 v222, v222
	v_add_f32_e32 v170, 1.0, v170
	v_mul_f32_e32 v224, 0xbfb8aa3b, v133
	v_rcp_f32_e32 v170, v170
	v_add_f32_e32 v220, 1.0, v220
	v_exp_f32_e32 v224, v224
	v_mul_f32_e32 v219, 0xbfb8aa3b, v126
	v_rcp_f32_e32 v220, v220
	v_exp_f32_e32 v219, v219
	v_mul_f32_e32 v221, 0xbfb8aa3b, v127
	v_add_f32_e32 v222, 1.0, v222
	v_exp_f32_e32 v221, v221
	v_rcp_f32_e32 v222, v222
	v_mul_f32_e32 v223, 0xbfb8aa3b, v128
	v_add_f32_e32 v224, 1.0, v224
	v_mul_f32_e32 v170, 0x437f0000, v170
	v_exp_f32_e32 v223, v223
	v_rcp_f32_e32 v224, v224
	v_mul_f32_e32 v220, 0x437f0000, v220
	v_add_f32_e32 v219, 1.0, v219
	v_mul_f32_e32 v225, 0xbfb8aa3b, v129
	v_cvt_pk_u8_f32 v170, v170, 0, 0
	v_rcp_f32_e32 v219, v219
	v_add_f32_e32 v221, 1.0, v221
	v_exp_f32_e32 v225, v225
	v_cvt_pk_u8_f32 v170, v220, 1, v170
	v_mul_f32_e32 v220, 0x437f0000, v222
	v_rcp_f32_e32 v221, v221
	v_add_f32_e32 v223, 1.0, v223
	v_cvt_pk_u8_f32 v170, v220, 2, v170
	v_mul_f32_e32 v220, 0x437f0000, v224
	v_rcp_f32_e32 v223, v223
	v_add_f32_e32 v225, 1.0, v225
	v_cvt_pk_u8_f32 v220, v220, 3, v170
	v_mul_f32_e32 v170, 0x437f0000, v219
	v_rcp_f32_e32 v225, v225
	v_mul_f32_e32 v219, 0x437f0000, v221
	v_cvt_pk_u8_f32 v170, v170, 0, 0
	v_cvt_pk_u8_f32 v170, v219, 1, v170
	v_mul_f32_e32 v219, 0x437f0000, v223
	v_cvt_pk_u8_f32 v170, v219, 2, v170
	v_mul_f32_e32 v219, 0x437f0000, v225
	v_lshlrev_b64 v[146:147], 11, v[184:185]
	v_lshl_add_u64 v[146:147], v[148:149], 0, v[146:147]
	v_cvt_pk_u8_f32 v221, v219, 3, v170
	v_add_f32_e32 v170, 1.0, v217
	global_store_dwordx2 v[146:147], v[220:221], off nt
	v_rcp_f32_e32 v170, v170
	v_add_f32_e32 v220, 1.0, v218
	v_rcp_f32_e32 v220, v220
	v_add_f32_e32 v222, 1.0, v154
	v_rcp_f32_e32 v222, v222
	v_add_f32_e32 v224, 1.0, v155
	v_mul_f32_e32 v170, 0x437f0000, v170
	v_rcp_f32_e32 v224, v224
	v_mul_f32_e32 v220, 0x437f0000, v220
	v_add_f32_e32 v219, 1.0, v152
	v_cvt_pk_u8_f32 v170, v170, 0, 0
	v_rcp_f32_e32 v219, v219
	v_add_f32_e32 v221, 1.0, v153
	v_cvt_pk_u8_f32 v170, v220, 1, v170
	v_mul_f32_e32 v220, 0x437f0000, v222
	v_rcp_f32_e32 v221, v221
	v_add_f32_e32 v223, 1.0, v150
	v_cvt_pk_u8_f32 v170, v220, 2, v170
	v_mul_f32_e32 v220, 0x437f0000, v224
	v_rcp_f32_e32 v223, v223
	v_add_f32_e32 v225, 1.0, v151
	v_cvt_pk_u8_f32 v220, v220, 3, v170
	v_mul_f32_e32 v170, 0x437f0000, v219
	v_rcp_f32_e32 v225, v225
	v_mul_f32_e32 v219, 0x437f0000, v221
	v_cvt_pk_u8_f32 v170, v170, 0, 0
	v_cvt_pk_u8_f32 v170, v219, 1, v170
	v_mul_f32_e32 v219, 0x437f0000, v223
	v_cvt_pk_u8_f32 v170, v219, 2, v170
	v_mul_f32_e32 v219, 0x437f0000, v225
	v_cvt_pk_u8_f32 v221, v219, 3, v170
	v_mul_f32_e32 v170, 0xbfb8aa3b, v110
	v_exp_f32_e32 v170, v170
	v_mul_f32_e32 v222, 0xbfb8aa3b, v111
	v_exp_f32_e32 v222, v222
	v_mul_f32_e32 v224, 0xbfb8aa3b, v112
	v_exp_f32_e32 v224, v224
	v_add_f32_e32 v170, 1.0, v170
	v_mul_f32_e32 v226, 0xbfb8aa3b, v113
	v_rcp_f32_e32 v170, v170
	v_add_f32_e32 v222, 1.0, v222
	v_exp_f32_e32 v226, v226
	v_mul_f32_e32 v219, 0xbfb8aa3b, v106
	v_rcp_f32_e32 v222, v222
	v_exp_f32_e32 v219, v219
	v_mul_f32_e32 v223, 0xbfb8aa3b, v107
	v_add_f32_e32 v224, 1.0, v224
	v_exp_f32_e32 v223, v223
	v_rcp_f32_e32 v224, v224
	v_mul_f32_e32 v225, 0xbfb8aa3b, v108
	v_add_f32_e32 v226, 1.0, v226
	v_mul_f32_e32 v170, 0x437f0000, v170
	v_exp_f32_e32 v225, v225
	v_rcp_f32_e32 v226, v226
	v_mul_f32_e32 v222, 0x437f0000, v222
	v_add_f32_e32 v219, 1.0, v219
	v_mul_f32_e32 v227, 0xbfb8aa3b, v109
	v_cvt_pk_u8_f32 v170, v170, 0, 0
	v_rcp_f32_e32 v219, v219
	v_add_f32_e32 v223, 1.0, v223
	v_exp_f32_e32 v227, v227
	v_cvt_pk_u8_f32 v170, v222, 1, v170
	v_mul_f32_e32 v222, 0x437f0000, v224
	v_rcp_f32_e32 v223, v223
	v_add_f32_e32 v225, 1.0, v225
	v_cvt_pk_u8_f32 v170, v222, 2, v170
	v_mul_f32_e32 v222, 0x437f0000, v226
	v_rcp_f32_e32 v225, v225
	v_add_f32_e32 v227, 1.0, v227
	v_cvt_pk_u8_f32 v222, v222, 3, v170
	v_mul_f32_e32 v170, 0x437f0000, v219
	v_rcp_f32_e32 v227, v227
	v_mul_f32_e32 v219, 0x437f0000, v223
	v_cvt_pk_u8_f32 v170, v170, 0, 0
	v_cvt_pk_u8_f32 v170, v219, 1, v170
	v_mul_f32_e32 v219, 0x437f0000, v225
	global_store_dwordx2 v[146:147], v[220:221], off offset:128 nt
	v_or_b32_e32 v220, 16, v184
	v_ashrrev_i32_e32 v221, 31, v220
	v_cvt_pk_u8_f32 v170, v219, 2, v170
	v_mul_f32_e32 v219, 0x437f0000, v227
	v_lshlrev_b64 v[220:221], 11, v[220:221]
	v_lshl_add_u64 v[220:221], v[148:149], 0, v[220:221]
	v_cvt_pk_u8_f32 v223, v219, 3, v170
	v_add_f32_e32 v170, 1.0, v215
	global_store_dwordx2 v[220:221], v[222:223], off nt
	v_rcp_f32_e32 v170, v170
	v_add_f32_e32 v222, 1.0, v216
	v_rcp_f32_e32 v222, v222
	v_add_f32_e32 v224, 1.0, v213
	v_rcp_f32_e32 v224, v224
	v_add_f32_e32 v226, 1.0, v214
	v_mul_f32_e32 v170, 0x437f0000, v170
	v_rcp_f32_e32 v226, v226
	v_mul_f32_e32 v222, 0x437f0000, v222
	v_add_f32_e32 v219, 1.0, v211
	v_cvt_pk_u8_f32 v170, v170, 0, 0
	v_rcp_f32_e32 v219, v219
	v_add_f32_e32 v223, 1.0, v212
	v_cvt_pk_u8_f32 v170, v222, 1, v170
	v_mul_f32_e32 v222, 0x437f0000, v224
	v_rcp_f32_e32 v223, v223
	v_add_f32_e32 v225, 1.0, v209
	v_cvt_pk_u8_f32 v170, v222, 2, v170
	v_mul_f32_e32 v222, 0x437f0000, v226
	v_rcp_f32_e32 v225, v225
	v_add_f32_e32 v227, 1.0, v210
	v_cvt_pk_u8_f32 v222, v222, 3, v170
	v_mul_f32_e32 v170, 0x437f0000, v219
	v_rcp_f32_e32 v227, v227
	v_mul_f32_e32 v219, 0x437f0000, v223
	v_cvt_pk_u8_f32 v170, v170, 0, 0
	v_cvt_pk_u8_f32 v170, v219, 1, v170
	v_mul_f32_e32 v219, 0x437f0000, v225
	v_cvt_pk_u8_f32 v170, v219, 2, v170
	v_mul_f32_e32 v219, 0x437f0000, v227
	v_cvt_pk_u8_f32 v223, v219, 3, v170
	v_mul_f32_e32 v170, 0xbfb8aa3b, v94
	global_store_dwordx2 v[220:221], v[222:223], off offset:128 nt
	v_exp_f32_e32 v170, v170
	v_mul_f32_e32 v222, 0xbfb8aa3b, v95
	v_exp_f32_e32 v222, v222
	v_mul_f32_e32 v224, 0xbfb8aa3b, v96
	v_exp_f32_e32 v224, v224
	v_add_f32_e32 v170, 1.0, v170
	v_mul_f32_e32 v226, 0xbfb8aa3b, v97
	v_rcp_f32_e32 v170, v170
	v_add_f32_e32 v222, 1.0, v222
	v_exp_f32_e32 v226, v226
	v_mul_f32_e32 v219, 0xbfb8aa3b, v90
	v_rcp_f32_e32 v222, v222
	v_exp_f32_e32 v219, v219
	v_mul_f32_e32 v223, 0xbfb8aa3b, v91
	v_add_f32_e32 v224, 1.0, v224
	v_exp_f32_e32 v223, v223
	v_rcp_f32_e32 v224, v224
	v_mul_f32_e32 v225, 0xbfb8aa3b, v92
	v_add_f32_e32 v226, 1.0, v226
	v_mul_f32_e32 v170, 0x437f0000, v170
	v_exp_f32_e32 v225, v225
	v_rcp_f32_e32 v226, v226
	v_mul_f32_e32 v222, 0x437f0000, v222
	v_add_f32_e32 v219, 1.0, v219
	v_mul_f32_e32 v227, 0xbfb8aa3b, v93
	v_cvt_pk_u8_f32 v170, v170, 0, 0
	v_rcp_f32_e32 v219, v219
	v_add_f32_e32 v223, 1.0, v223
	v_exp_f32_e32 v227, v227
	v_cvt_pk_u8_f32 v170, v222, 1, v170
	v_mul_f32_e32 v222, 0x437f0000, v224
	v_rcp_f32_e32 v223, v223
	v_add_f32_e32 v225, 1.0, v225
	v_cvt_pk_u8_f32 v170, v222, 2, v170
	v_mul_f32_e32 v222, 0x437f0000, v226
	v_rcp_f32_e32 v225, v225
	v_add_f32_e32 v227, 1.0, v227
	v_cvt_pk_u8_f32 v222, v222, 3, v170
	v_mul_f32_e32 v170, 0x437f0000, v219
	v_rcp_f32_e32 v227, v227
	v_mul_f32_e32 v219, 0x437f0000, v223
	v_cvt_pk_u8_f32 v170, v170, 0, 0
	v_cvt_pk_u8_f32 v170, v219, 1, v170
	v_mul_f32_e32 v219, 0x437f0000, v225
	v_or_b32_e32 v220, 32, v184
	v_ashrrev_i32_e32 v221, 31, v220
	v_cvt_pk_u8_f32 v170, v219, 2, v170
	v_mul_f32_e32 v219, 0x437f0000, v227
	v_lshlrev_b64 v[220:221], 11, v[220:221]
	v_lshl_add_u64 v[220:221], v[148:149], 0, v[220:221]
	v_cvt_pk_u8_f32 v223, v219, 3, v170
	v_add_f32_e32 v170, 1.0, v207
	global_store_dwordx2 v[220:221], v[222:223], off nt
	v_rcp_f32_e32 v170, v170
	v_add_f32_e32 v222, 1.0, v208
	v_rcp_f32_e32 v222, v222
	v_add_f32_e32 v224, 1.0, v205
	v_rcp_f32_e32 v224, v224
	v_add_f32_e32 v226, 1.0, v206
	v_mul_f32_e32 v170, 0x437f0000, v170
	v_rcp_f32_e32 v226, v226
	v_mul_f32_e32 v222, 0x437f0000, v222
	v_add_f32_e32 v219, 1.0, v190
	v_cvt_pk_u8_f32 v170, v170, 0, 0
	v_rcp_f32_e32 v219, v219
	v_add_f32_e32 v223, 1.0, v191
	v_cvt_pk_u8_f32 v170, v222, 1, v170
	v_mul_f32_e32 v222, 0x437f0000, v224
	v_rcp_f32_e32 v223, v223
	v_add_f32_e32 v225, 1.0, v156
	v_cvt_pk_u8_f32 v170, v222, 2, v170
	v_mul_f32_e32 v222, 0x437f0000, v226
	v_rcp_f32_e32 v225, v225
	v_add_f32_e32 v227, 1.0, v157
	v_cvt_pk_u8_f32 v222, v222, 3, v170
	v_mul_f32_e32 v170, 0x437f0000, v219
	v_rcp_f32_e32 v227, v227
	v_mul_f32_e32 v219, 0x437f0000, v223
	v_cvt_pk_u8_f32 v170, v170, 0, 0
	v_cvt_pk_u8_f32 v170, v219, 1, v170
	v_mul_f32_e32 v219, 0x437f0000, v225
	v_cvt_pk_u8_f32 v170, v219, 2, v170
	v_mul_f32_e32 v219, 0x437f0000, v227
	v_cvt_pk_u8_f32 v223, v219, 3, v170
	global_store_dwordx2 v[220:221], v[222:223], off offset:128 nt
	v_or_b32_e32 v220, 48, v184
	v_ashrrev_i32_e32 v221, 31, v220
	v_lshlrev_b64 v[220:221], 11, v[220:221]
	v_mul_f32_e32 v170, 0xbfb8aa3b, v78
	v_exp_f32_e32 v170, v170
	v_lshl_add_u64 v[148:149], v[148:149], 0, v[220:221]
	v_mul_f32_e32 v220, 0xbfb8aa3b, v79
	v_exp_f32_e32 v220, v220
	v_mul_f32_e32 v222, 0xbfb8aa3b, v80
	v_exp_f32_e32 v222, v222
	v_add_f32_e32 v170, 1.0, v170
	v_mul_f32_e32 v224, 0xbfb8aa3b, v81
	v_rcp_f32_e32 v170, v170
	v_add_f32_e32 v220, 1.0, v220
	v_exp_f32_e32 v224, v224
	v_mul_f32_e32 v219, 0xbfb8aa3b, v74
	v_rcp_f32_e32 v220, v220
	v_exp_f32_e32 v219, v219
	v_mul_f32_e32 v221, 0xbfb8aa3b, v75
	v_add_f32_e32 v222, 1.0, v222
	v_exp_f32_e32 v221, v221
	v_rcp_f32_e32 v222, v222
	v_mul_f32_e32 v223, 0xbfb8aa3b, v76
	v_add_f32_e32 v224, 1.0, v224
	v_mul_f32_e32 v170, 0x437f0000, v170
	v_exp_f32_e32 v223, v223
	v_rcp_f32_e32 v224, v224
	v_mul_f32_e32 v220, 0x437f0000, v220
	v_add_f32_e32 v219, 1.0, v219
	v_mul_f32_e32 v225, 0xbfb8aa3b, v77
	v_cvt_pk_u8_f32 v170, v170, 0, 0
	v_rcp_f32_e32 v219, v219
	v_add_f32_e32 v221, 1.0, v221
	v_exp_f32_e32 v225, v225
	v_cvt_pk_u8_f32 v170, v220, 1, v170
	v_mul_f32_e32 v220, 0x437f0000, v222
	v_rcp_f32_e32 v221, v221
	v_add_f32_e32 v223, 1.0, v223
	v_cvt_pk_u8_f32 v170, v220, 2, v170
	v_mul_f32_e32 v220, 0x437f0000, v224
	v_rcp_f32_e32 v223, v223
	v_add_f32_e32 v225, 1.0, v225
	v_cvt_pk_u8_f32 v220, v220, 3, v170
	v_mul_f32_e32 v170, 0x437f0000, v219
	v_rcp_f32_e32 v225, v225
	v_mul_f32_e32 v219, 0x437f0000, v221
	v_cvt_pk_u8_f32 v170, v170, 0, 0
	v_cvt_pk_u8_f32 v170, v219, 1, v170
	v_mul_f32_e32 v219, 0x437f0000, v223
	v_cvt_pk_u8_f32 v170, v219, 2, v170
	v_mul_f32_e32 v219, 0x437f0000, v225
	v_cvt_pk_u8_f32 v221, v219, 3, v170
	v_add_f32_e32 v170, 1.0, v188
	global_store_dwordx2 v[148:149], v[220:221], off nt
	v_rcp_f32_e32 v170, v170
	v_add_f32_e32 v220, 1.0, v189
	v_rcp_f32_e32 v220, v220
	v_add_f32_e32 v222, 1.0, v186
	v_rcp_f32_e32 v222, v222
	v_add_f32_e32 v224, 1.0, v187
	v_mul_f32_e32 v170, 0x437f0000, v170
	v_rcp_f32_e32 v224, v224
	v_mul_f32_e32 v220, 0x437f0000, v220
	v_add_f32_e32 v219, 1.0, v160
	v_cvt_pk_u8_f32 v170, v170, 0, 0
	v_rcp_f32_e32 v219, v219
	v_add_f32_e32 v221, 1.0, v161
	v_cvt_pk_u8_f32 v170, v220, 1, v170
	v_mul_f32_e32 v220, 0x437f0000, v222
	v_rcp_f32_e32 v221, v221
	v_add_f32_e32 v223, 1.0, v158
	v_cvt_pk_u8_f32 v170, v220, 2, v170
	v_mul_f32_e32 v220, 0x437f0000, v224
	v_rcp_f32_e32 v223, v223
	v_add_f32_e32 v225, 1.0, v159
	v_cvt_pk_u8_f32 v220, v220, 3, v170
	v_mul_f32_e32 v170, 0x437f0000, v219
	v_rcp_f32_e32 v225, v225
	v_mul_f32_e32 v219, 0x437f0000, v221
	v_cvt_pk_u8_f32 v170, v170, 0, 0
	v_cvt_pk_u8_f32 v170, v219, 1, v170
	v_mul_f32_e32 v219, 0x437f0000, v223
	v_cvt_pk_u8_f32 v170, v219, 2, v170
	v_mul_f32_e32 v219, 0x437f0000, v225
	v_cvt_pk_u8_f32 v221, v219, 3, v170
	s_cmpk_gt_i32 s53, 0x154f
	global_store_dwordx2 v[148:149], v[220:221], off offset:128 nt
	s_cbranch_scc1 .LBB0_413
	s_waitcnt vmcnt(8)
	global_store_dwordx4 v[248:249], v[114:117], off nt
	global_store_dwordx4 v[250:251], v[134:137], off nt
	global_store_dwordx4 v[252:253], v[138:141], off nt
	global_store_dwordx4 v[254:255], v[142:145], off nt
.LBB0_413:
	v_mul_f32_e32 v148, 0xbfb8aa3b, v62
	v_exp_f32_e32 v170, v148
	v_mul_f32_e32 v220, 0xbfb8aa3b, v63
	v_exp_f32_e32 v220, v220
	v_mul_f32_e32 v222, 0xbfb8aa3b, v64
	v_exp_f32_e32 v222, v222
	v_add_f32_e32 v170, 1.0, v170
	v_mul_f32_e32 v224, 0xbfb8aa3b, v65
	v_rcp_f32_e32 v170, v170
	v_add_f32_e32 v220, 1.0, v220
	v_exp_f32_e32 v224, v224
	v_mul_f32_e32 v148, 0xbfb8aa3b, v58
	v_rcp_f32_e32 v220, v220
	v_exp_f32_e32 v219, v148
	v_mul_f32_e32 v221, 0xbfb8aa3b, v59
	v_add_f32_e32 v222, 1.0, v222
	v_exp_f32_e32 v221, v221
	v_rcp_f32_e32 v222, v222
	v_mul_f32_e32 v223, 0xbfb8aa3b, v60
	v_add_f32_e32 v224, 1.0, v224
	v_mul_f32_e32 v170, 0x437f0000, v170
	v_exp_f32_e32 v223, v223
	v_rcp_f32_e32 v224, v224
	v_mul_f32_e32 v220, 0x437f0000, v220
	v_add_f32_e32 v219, 1.0, v219
	v_mul_f32_e32 v225, 0xbfb8aa3b, v61
	v_cvt_pk_u8_f32 v170, v170, 0, 0
	v_rcp_f32_e32 v219, v219
	v_add_f32_e32 v221, 1.0, v221
	v_exp_f32_e32 v225, v225
	v_cvt_pk_u8_f32 v170, v220, 1, v170
	v_mul_f32_e32 v220, 0x437f0000, v222
	v_rcp_f32_e32 v221, v221
	v_add_f32_e32 v223, 1.0, v223
	v_cvt_pk_u8_f32 v170, v220, 2, v170
	v_mul_f32_e32 v220, 0x437f0000, v224
	v_rcp_f32_e32 v223, v223
	v_add_f32_e32 v225, 1.0, v225
	v_cvt_pk_u8_f32 v220, v220, 3, v170
	v_mul_f32_e32 v170, 0x437f0000, v219
	v_rcp_f32_e32 v225, v225
	v_mul_f32_e32 v219, 0x437f0000, v221
	v_cvt_pk_u8_f32 v170, v170, 0, 0
	v_cvt_pk_u8_f32 v170, v219, 1, v170
	v_mul_f32_e32 v219, 0x437f0000, v223
	s_mov_b64 s[0:1], 0x40000
	v_lshl_add_u64 v[148:149], v[146:147], 0, s[0:1]
	v_cvt_pk_u8_f32 v170, v219, 2, v170
	v_mul_f32_e32 v219, 0x437f0000, v225
	s_mov_b32 s0, 0x40000
	v_add_co_u32_e32 v222, vcc, s0, v146
	v_cvt_pk_u8_f32 v221, v219, 3, v170
	s_nop 0
	v_addc_co_u32_e32 v223, vcc, 0, v147, vcc
	v_mul_f32_e32 v170, 0xbfb8aa3b, v54
	v_exp_f32_e32 v170, v170
	global_store_dwordx2 v[222:223], v[220:221], off nt
	v_mul_f32_e32 v220, 0xbfb8aa3b, v55
	v_exp_f32_e32 v220, v220
	v_mul_f32_e32 v222, 0xbfb8aa3b, v56
	v_exp_f32_e32 v222, v222
	v_add_f32_e32 v170, 1.0, v170
	v_mul_f32_e32 v224, 0xbfb8aa3b, v57
	v_rcp_f32_e32 v170, v170
	v_add_f32_e32 v220, 1.0, v220
	v_exp_f32_e32 v224, v224
	v_mul_f32_e32 v219, 0xbfb8aa3b, v50
	v_rcp_f32_e32 v220, v220
	v_exp_f32_e32 v219, v219
	v_mul_f32_e32 v221, 0xbfb8aa3b, v51
	v_add_f32_e32 v222, 1.0, v222
	v_exp_f32_e32 v221, v221
	v_rcp_f32_e32 v222, v222
	v_mul_f32_e32 v223, 0xbfb8aa3b, v52
	v_add_f32_e32 v224, 1.0, v224
	v_mul_f32_e32 v170, 0x437f0000, v170
	v_exp_f32_e32 v223, v223
	v_rcp_f32_e32 v224, v224
	v_mul_f32_e32 v220, 0x437f0000, v220
	v_add_f32_e32 v219, 1.0, v219
	v_mul_f32_e32 v225, 0xbfb8aa3b, v53
	v_cvt_pk_u8_f32 v170, v170, 0, 0
	v_rcp_f32_e32 v219, v219
	v_add_f32_e32 v221, 1.0, v221
	v_exp_f32_e32 v225, v225
	v_cvt_pk_u8_f32 v170, v220, 1, v170
	v_mul_f32_e32 v220, 0x437f0000, v222
	v_rcp_f32_e32 v221, v221
	v_add_f32_e32 v223, 1.0, v223
	v_cvt_pk_u8_f32 v170, v220, 2, v170
	v_mul_f32_e32 v220, 0x437f0000, v224
	v_rcp_f32_e32 v223, v223
	v_add_f32_e32 v225, 1.0, v225
	v_cvt_pk_u8_f32 v220, v220, 3, v170
	v_mul_f32_e32 v170, 0x437f0000, v219
	v_rcp_f32_e32 v225, v225
	v_mul_f32_e32 v219, 0x437f0000, v221
	v_cvt_pk_u8_f32 v170, v170, 0, 0
	v_cvt_pk_u8_f32 v170, v219, 1, v170
	v_mul_f32_e32 v219, 0x437f0000, v223
	v_cvt_pk_u8_f32 v170, v219, 2, v170
	v_mul_f32_e32 v219, 0x437f0000, v225
	v_cvt_pk_u8_f32 v221, v219, 3, v170
	global_store_dwordx2 v[148:149], v[220:221], off offset:128 nt
	v_mul_f32_e32 v148, 0xbfb8aa3b, v46
	v_exp_f32_e32 v170, v148
	v_mul_f32_e32 v220, 0xbfb8aa3b, v47
	v_exp_f32_e32 v220, v220
	v_mul_f32_e32 v222, 0xbfb8aa3b, v48
	v_exp_f32_e32 v222, v222
	v_add_f32_e32 v170, 1.0, v170
	v_mul_f32_e32 v224, 0xbfb8aa3b, v49
	v_rcp_f32_e32 v170, v170
	v_add_f32_e32 v220, 1.0, v220
	v_exp_f32_e32 v224, v224
	v_mul_f32_e32 v148, 0xbfb8aa3b, v42
	v_rcp_f32_e32 v220, v220
	v_exp_f32_e32 v219, v148
	v_mul_f32_e32 v221, 0xbfb8aa3b, v43
	v_add_f32_e32 v222, 1.0, v222
	v_exp_f32_e32 v221, v221
	v_rcp_f32_e32 v222, v222
	v_mul_f32_e32 v223, 0xbfb8aa3b, v44
	v_add_f32_e32 v224, 1.0, v224
	v_mul_f32_e32 v170, 0x437f0000, v170
	v_exp_f32_e32 v223, v223
	v_rcp_f32_e32 v224, v224
	v_mul_f32_e32 v220, 0x437f0000, v220
	v_add_f32_e32 v219, 1.0, v219
	v_mul_f32_e32 v225, 0xbfb8aa3b, v45
	v_cvt_pk_u8_f32 v170, v170, 0, 0
	v_rcp_f32_e32 v219, v219
	v_add_f32_e32 v221, 1.0, v221
	v_exp_f32_e32 v225, v225
	v_cvt_pk_u8_f32 v170, v220, 1, v170
	v_mul_f32_e32 v220, 0x437f0000, v222
	v_rcp_f32_e32 v221, v221
	v_add_f32_e32 v223, 1.0, v223
	v_cvt_pk_u8_f32 v170, v220, 2, v170
	v_mul_f32_e32 v220, 0x437f0000, v224
	v_rcp_f32_e32 v223, v223
	v_add_f32_e32 v225, 1.0, v225
	v_cvt_pk_u8_f32 v220, v220, 3, v170
	v_mul_f32_e32 v170, 0x437f0000, v219
	v_rcp_f32_e32 v225, v225
	v_mul_f32_e32 v219, 0x437f0000, v221
	v_cvt_pk_u8_f32 v170, v170, 0, 0
	v_cvt_pk_u8_f32 v170, v219, 1, v170
	v_mul_f32_e32 v219, 0x437f0000, v223
	s_mov_b64 s[0:1], 0x48000
	v_lshl_add_u64 v[148:149], v[146:147], 0, s[0:1]
	v_cvt_pk_u8_f32 v170, v219, 2, v170
	v_mul_f32_e32 v219, 0x437f0000, v225
	s_mov_b32 s0, 0x48000
	v_add_co_u32_e32 v222, vcc, s0, v146
	v_cvt_pk_u8_f32 v221, v219, 3, v170
	s_nop 0
	v_addc_co_u32_e32 v223, vcc, 0, v147, vcc
	v_mul_f32_e32 v170, 0xbfb8aa3b, v38
	v_exp_f32_e32 v170, v170
	global_store_dwordx2 v[222:223], v[220:221], off nt
	v_mul_f32_e32 v220, 0xbfb8aa3b, v39
	v_exp_f32_e32 v220, v220
	v_mul_f32_e32 v222, 0xbfb8aa3b, v40
	v_exp_f32_e32 v222, v222
	v_add_f32_e32 v170, 1.0, v170
	v_mul_f32_e32 v224, 0xbfb8aa3b, v41
	v_rcp_f32_e32 v170, v170
	v_add_f32_e32 v220, 1.0, v220
	v_exp_f32_e32 v224, v224
	v_mul_f32_e32 v219, 0xbfb8aa3b, v34
	v_rcp_f32_e32 v220, v220
	v_exp_f32_e32 v219, v219
	v_mul_f32_e32 v221, 0xbfb8aa3b, v35
	v_add_f32_e32 v222, 1.0, v222
	v_exp_f32_e32 v221, v221
	v_rcp_f32_e32 v222, v222
	v_mul_f32_e32 v223, 0xbfb8aa3b, v36
	v_add_f32_e32 v224, 1.0, v224
	v_mul_f32_e32 v170, 0x437f0000, v170
	v_exp_f32_e32 v223, v223
	v_rcp_f32_e32 v224, v224
	v_mul_f32_e32 v220, 0x437f0000, v220
	v_add_f32_e32 v219, 1.0, v219
	v_mul_f32_e32 v225, 0xbfb8aa3b, v37
	v_cvt_pk_u8_f32 v170, v170, 0, 0
	v_rcp_f32_e32 v219, v219
	v_add_f32_e32 v221, 1.0, v221
	v_exp_f32_e32 v225, v225
	v_cvt_pk_u8_f32 v170, v220, 1, v170
	v_mul_f32_e32 v220, 0x437f0000, v222
	v_rcp_f32_e32 v221, v221
	v_add_f32_e32 v223, 1.0, v223
	v_cvt_pk_u8_f32 v170, v220, 2, v170
	v_mul_f32_e32 v220, 0x437f0000, v224
	v_rcp_f32_e32 v223, v223
	v_add_f32_e32 v225, 1.0, v225
	v_cvt_pk_u8_f32 v220, v220, 3, v170
	v_mul_f32_e32 v170, 0x437f0000, v219
	v_rcp_f32_e32 v225, v225
	v_mul_f32_e32 v219, 0x437f0000, v221
	v_cvt_pk_u8_f32 v170, v170, 0, 0
	v_cvt_pk_u8_f32 v170, v219, 1, v170
	v_mul_f32_e32 v219, 0x437f0000, v223
	v_cvt_pk_u8_f32 v170, v219, 2, v170
	v_mul_f32_e32 v219, 0x437f0000, v225
	v_cvt_pk_u8_f32 v221, v219, 3, v170
	global_store_dwordx2 v[148:149], v[220:221], off offset:128 nt
	v_mul_f32_e32 v148, 0xbfb8aa3b, v30
	v_exp_f32_e32 v170, v148
	v_mul_f32_e32 v220, 0xbfb8aa3b, v31
	v_exp_f32_e32 v220, v220
	v_mul_f32_e32 v222, 0xbfb8aa3b, v32
	v_exp_f32_e32 v222, v222
	v_add_f32_e32 v170, 1.0, v170
	v_mul_f32_e32 v224, 0xbfb8aa3b, v33
	v_rcp_f32_e32 v170, v170
	v_add_f32_e32 v220, 1.0, v220
	v_exp_f32_e32 v224, v224
	v_mul_f32_e32 v148, 0xbfb8aa3b, v26
	v_rcp_f32_e32 v220, v220
	v_exp_f32_e32 v219, v148
	v_mul_f32_e32 v221, 0xbfb8aa3b, v27
	v_add_f32_e32 v222, 1.0, v222
	v_exp_f32_e32 v221, v221
	v_rcp_f32_e32 v222, v222
	v_mul_f32_e32 v223, 0xbfb8aa3b, v28
	v_add_f32_e32 v224, 1.0, v224
	v_mul_f32_e32 v170, 0x437f0000, v170
	v_exp_f32_e32 v223, v223
	v_rcp_f32_e32 v224, v224
	v_mul_f32_e32 v220, 0x437f0000, v220
	v_add_f32_e32 v219, 1.0, v219
	v_mul_f32_e32 v225, 0xbfb8aa3b, v29
	v_cvt_pk_u8_f32 v170, v170, 0, 0
	v_rcp_f32_e32 v219, v219
	v_add_f32_e32 v221, 1.0, v221
	v_exp_f32_e32 v225, v225
	v_cvt_pk_u8_f32 v170, v220, 1, v170
	v_mul_f32_e32 v220, 0x437f0000, v222
	v_rcp_f32_e32 v221, v221
	v_add_f32_e32 v223, 1.0, v223
	v_cvt_pk_u8_f32 v170, v220, 2, v170
	v_mul_f32_e32 v220, 0x437f0000, v224
	v_rcp_f32_e32 v223, v223
	v_add_f32_e32 v225, 1.0, v225
	v_cvt_pk_u8_f32 v220, v220, 3, v170
	v_mul_f32_e32 v170, 0x437f0000, v219
	v_rcp_f32_e32 v225, v225
	v_mul_f32_e32 v219, 0x437f0000, v221
	v_cvt_pk_u8_f32 v170, v170, 0, 0
	v_cvt_pk_u8_f32 v170, v219, 1, v170
	v_mul_f32_e32 v219, 0x437f0000, v223
	s_mov_b64 s[0:1], 0x50000
	v_lshl_add_u64 v[148:149], v[146:147], 0, s[0:1]
	v_cvt_pk_u8_f32 v170, v219, 2, v170
	v_mul_f32_e32 v219, 0x437f0000, v225
	s_mov_b32 s0, 0x50000
	v_add_co_u32_e32 v222, vcc, s0, v146
	v_cvt_pk_u8_f32 v221, v219, 3, v170
	s_nop 0
	v_addc_co_u32_e32 v223, vcc, 0, v147, vcc
	v_mul_f32_e32 v170, 0xbfb8aa3b, v22
	v_exp_f32_e32 v170, v170
	global_store_dwordx2 v[222:223], v[220:221], off nt
	v_mul_f32_e32 v220, 0xbfb8aa3b, v23
	v_exp_f32_e32 v220, v220
	v_mul_f32_e32 v222, 0xbfb8aa3b, v24
	v_exp_f32_e32 v222, v222
	v_add_f32_e32 v170, 1.0, v170
	v_mul_f32_e32 v224, 0xbfb8aa3b, v25
	v_rcp_f32_e32 v170, v170
	v_add_f32_e32 v220, 1.0, v220
	v_exp_f32_e32 v224, v224
	v_mul_f32_e32 v219, 0xbfb8aa3b, v18
	v_rcp_f32_e32 v220, v220
	v_exp_f32_e32 v219, v219
	v_mul_f32_e32 v221, 0xbfb8aa3b, v19
	v_add_f32_e32 v222, 1.0, v222
	v_exp_f32_e32 v221, v221
	v_rcp_f32_e32 v222, v222
	v_mul_f32_e32 v223, 0xbfb8aa3b, v20
	v_add_f32_e32 v224, 1.0, v224
	v_mul_f32_e32 v170, 0x437f0000, v170
	v_exp_f32_e32 v223, v223
	v_rcp_f32_e32 v224, v224
	v_mul_f32_e32 v220, 0x437f0000, v220
	v_add_f32_e32 v219, 1.0, v219
	v_mul_f32_e32 v225, 0xbfb8aa3b, v21
	v_cvt_pk_u8_f32 v170, v170, 0, 0
	v_rcp_f32_e32 v219, v219
	v_add_f32_e32 v221, 1.0, v221
	v_exp_f32_e32 v225, v225
	v_cvt_pk_u8_f32 v170, v220, 1, v170
	v_mul_f32_e32 v220, 0x437f0000, v222
	v_rcp_f32_e32 v221, v221
	v_add_f32_e32 v223, 1.0, v223
	v_cvt_pk_u8_f32 v170, v220, 2, v170
	v_mul_f32_e32 v220, 0x437f0000, v224
	v_rcp_f32_e32 v223, v223
	v_add_f32_e32 v225, 1.0, v225
	v_cvt_pk_u8_f32 v220, v220, 3, v170
	v_mul_f32_e32 v170, 0x437f0000, v219
	v_rcp_f32_e32 v225, v225
	v_mul_f32_e32 v219, 0x437f0000, v221
	v_cvt_pk_u8_f32 v170, v170, 0, 0
	v_cvt_pk_u8_f32 v170, v219, 1, v170
	v_mul_f32_e32 v219, 0x437f0000, v223
	v_cvt_pk_u8_f32 v170, v219, 2, v170
	v_mul_f32_e32 v219, 0x437f0000, v225
	v_cvt_pk_u8_f32 v221, v219, 3, v170
	global_store_dwordx2 v[148:149], v[220:221], off offset:128 nt
	v_mul_f32_e32 v148, 0xbfb8aa3b, v14
	v_exp_f32_e32 v170, v148
	v_mul_f32_e32 v220, 0xbfb8aa3b, v15
	v_exp_f32_e32 v220, v220
	v_mul_f32_e32 v222, 0xbfb8aa3b, v16
	v_exp_f32_e32 v222, v222
	v_add_f32_e32 v170, 1.0, v170
	v_mul_f32_e32 v224, 0xbfb8aa3b, v17
	v_rcp_f32_e32 v170, v170
	v_add_f32_e32 v220, 1.0, v220
	v_exp_f32_e32 v224, v224
	v_mul_f32_e32 v148, 0xbfb8aa3b, v10
	v_rcp_f32_e32 v220, v220
	v_exp_f32_e32 v219, v148
	v_mul_f32_e32 v221, 0xbfb8aa3b, v11
	v_add_f32_e32 v222, 1.0, v222
	v_exp_f32_e32 v221, v221
	v_rcp_f32_e32 v222, v222
	v_mul_f32_e32 v223, 0xbfb8aa3b, v12
	v_add_f32_e32 v224, 1.0, v224
	v_mul_f32_e32 v170, 0x437f0000, v170
	v_exp_f32_e32 v223, v223
	v_rcp_f32_e32 v224, v224
	v_mul_f32_e32 v220, 0x437f0000, v220
	v_add_f32_e32 v219, 1.0, v219
	v_mul_f32_e32 v225, 0xbfb8aa3b, v13
	v_cvt_pk_u8_f32 v170, v170, 0, 0
	v_rcp_f32_e32 v219, v219
	v_add_f32_e32 v221, 1.0, v221
	v_exp_f32_e32 v225, v225
	v_cvt_pk_u8_f32 v170, v220, 1, v170
	v_mul_f32_e32 v220, 0x437f0000, v222
	v_rcp_f32_e32 v221, v221
	v_add_f32_e32 v223, 1.0, v223
	v_cvt_pk_u8_f32 v170, v220, 2, v170
	v_mul_f32_e32 v220, 0x437f0000, v224
	v_rcp_f32_e32 v223, v223
	v_add_f32_e32 v225, 1.0, v225
	v_cvt_pk_u8_f32 v220, v220, 3, v170
	v_mul_f32_e32 v170, 0x437f0000, v219
	v_rcp_f32_e32 v225, v225
	v_mul_f32_e32 v219, 0x437f0000, v221
	v_cvt_pk_u8_f32 v170, v170, 0, 0
	v_cvt_pk_u8_f32 v170, v219, 1, v170
	v_mul_f32_e32 v219, 0x437f0000, v223
	v_cvt_pk_u8_f32 v170, v219, 2, v170
	v_mul_f32_e32 v219, 0x437f0000, v225
	v_cvt_pk_u8_f32 v221, v219, 3, v170
	v_mul_f32_e32 v170, 0xbfb8aa3b, v6
	s_mov_b64 s[0:1], 0x58000
	v_exp_f32_e32 v170, v170
	v_lshl_add_u64 v[148:149], v[146:147], 0, s[0:1]
	s_mov_b32 s0, 0x58000
	v_add_co_u32_e32 v146, vcc, s0, v146
	v_mul_f32_e32 v219, 0xbfb8aa3b, v2
	s_nop 0
	v_addc_co_u32_e32 v147, vcc, 0, v147, vcc
	global_store_dwordx2 v[146:147], v[220:221], off nt
	v_add_f32_e32 v146, 1.0, v170
	v_mul_f32_e32 v170, 0xbfb8aa3b, v7
	v_exp_f32_e32 v170, v170
	v_exp_f32_e32 v219, v219
	v_mul_f32_e32 v220, 0xbfb8aa3b, v8
	v_exp_f32_e32 v220, v220
	v_mul_f32_e32 v222, 0xbfb8aa3b, v9
	v_rcp_f32_e32 v146, v146
	v_add_f32_e32 v170, 1.0, v170
	v_exp_f32_e32 v222, v222
	v_add_f32_e32 v147, 1.0, v219
	v_mul_f32_e32 v219, 0xbfb8aa3b, v3
	v_rcp_f32_e32 v170, v170
	v_exp_f32_e32 v219, v219
	v_add_f32_e32 v220, 1.0, v220
	v_mul_f32_e32 v221, 0xbfb8aa3b, v4
	v_rcp_f32_e32 v220, v220
	v_exp_f32_e32 v221, v221
	v_add_f32_e32 v222, 1.0, v222
	v_mul_f32_e32 v146, 0x437f0000, v146
	v_mul_f32_e32 v223, 0xbfb8aa3b, v5
	v_rcp_f32_e32 v222, v222
	v_mul_f32_e32 v170, 0x437f0000, v170
	v_rcp_f32_e32 v147, v147
	v_add_f32_e32 v219, 1.0, v219
	v_exp_f32_e32 v223, v223
	v_cvt_pk_u8_f32 v146, v146, 0, 0
	v_rcp_f32_e32 v219, v219
	v_cvt_pk_u8_f32 v146, v170, 1, v146
	v_mul_f32_e32 v170, 0x437f0000, v220
	v_add_f32_e32 v221, 1.0, v221
	v_rcp_f32_e32 v221, v221
	v_cvt_pk_u8_f32 v146, v170, 2, v146
	v_mul_f32_e32 v170, 0x437f0000, v222
	v_add_f32_e32 v223, 1.0, v223
	v_mul_f32_e32 v147, 0x437f0000, v147
	v_rcp_f32_e32 v223, v223
	v_cvt_pk_u8_f32 v146, v170, 3, v146
	v_mul_f32_e32 v170, 0x437f0000, v219
	v_cvt_pk_u8_f32 v147, v147, 0, 0
	v_cvt_pk_u8_f32 v147, v170, 1, v147
	v_mul_f32_e32 v170, 0x437f0000, v221
	v_cvt_pk_u8_f32 v147, v170, 2, v147
	v_mul_f32_e32 v170, 0x437f0000, v223
	v_cvt_pk_u8_f32 v147, v170, 3, v147
	global_store_dwordx2 v[148:149], v[146:147], off offset:128 nt
	s_mov_b64 s[2:3], 0
